# pair barrier + P1 tile order in two phases only (XCD pairs 0,1 start at round 0, pairs 2,3 at round 4)
# speedup vs baseline: 1.0104x; 1.0104x over previous
;     __host__ __device__ bool next(int i, Unit& u) const {
;         const long L = (long)i * G + c; if (L >= nwg) return false;
;         int wgid = (int)L; { const int q = nwg / NXCD, r = nwg % NXCD, xcd = wgid % NXCD, off = wgid / NXCD; wgid = (xcd < r ? xcd * (q + 1) : r * (q + 1) + (xcd - r) * q) + off; }
;         const int nig = WGM * nN, gid = wgid / nig, fm = gid * WGM, gsz = (nM - fm) < WGM ? (nM - fm) : WGM;
;         u.pm = fm + ((wgid % nig) % gsz); u.pn = (wgid % nig) / gsz; return true;
.LBB0_151:
	s_ashr_i32 s2, s12, 3
	s_add_i32 s2, s17, s2
	s_ashr_i32 s3, s2, 31
	s_lshr_b32 s3, s3, 24
	s_add_i32 s3, s2, s3
	s_ashr_i32 s12, s3, 8
	s_and_b32 s3, s3, 0xff00
	s_sub_i32 s2, s2, s3
	s_sext_i32_i16 s3, s2
	s_bfe_u32 s3, s3, 0x3001c
	s_add_i32 s3, s2, s3
	s_sext_i32_i16 s16, s3
	s_and_b32 s3, s3, 0xfff8
	s_sub_i32 s2, s2, s3
	s_lshl_b32 s12, s12, 3
	s_sext_i32_i16 s2, s2
	s_add_i32 s52, s12, s2
	s_ashr_i32 s42, s16, 3
	s_cmp_lg_u32 s98, 0
	s_cbranch_scc0 .Lrot_skip0
	s_bfe_u32 s2, s1, 0x10002
	s_lshl_b32 s2, s2, 4
	s_add_i32 s42, s42, s2

;     __host__ __device__ bool next(int i, Unit& u) const {
;         const long L = (long)i * G + c; if (L >= nwg) return false;
;         int wgid = (int)L; { const int q = nwg / NXCD, r = nwg % NXCD, xcd = wgid % NXCD, off = wgid / NXCD; wgid = (xcd < r ? xcd * (q + 1) : r * (q + 1) + (xcd - r) * q) + off; }
.LBB0_158:
	s_add_i32 s68, s68, 1
	s_mul_i32 s4, s68, s79
	s_mul_hi_u32 s12, s68, s80
	s_add_i32 s12, s12, s4
	s_mul_i32 s4, s68, s80
	s_add_u32 s36, s4, s1
	s_addc_u32 s37, s12, s13
	v_mov_b64_e32 v[2:3], 0x7ff
	v_cmp_gt_i64_e32 vcc, s[36:37], v[2:3]
	v_cmp_lt_i64_e64 s[38:39], s[36:37], v[236:237]
	s_cbranch_vccnz .LBB0_164
	s_cmp_lg_u32 s98, 0
	s_cbranch_scc0 .Lrot_skip1
	s_bfe_u32 s4, s1, 0x10002
	s_lshl_b32 s4, s4, 2
	s_add_i32 s4, s4, s68
	s_and_b32 s4, s4, 7
	s_mul_i32 s4, s4, s80
	s_add_i32 s36, s4, s1
